# prep phase: item relabeling for load balance (rwkv tiles spread evenly)
# speedup vs baseline: 1.0053x; 1.0053x over previous
.LBB0_375:
	s_sub_u32 s0, s76, 0x400
	s_cmp_lt_u32 s0, 0x200
	s_sub_i32 s0, 0x9ff, s76
	s_cselect_b32 s76, s0, s76
	s_add_i32 s76, s76, s94
	s_cmpk_lt_i32 s76, 0xd80
	s_cbranch_scc0 .LBB0_371
.LBB0_376:
	s_sub_u32 s0, s76, 0x400
	s_cmp_lt_u32 s0, 0x200
	s_sub_i32 s0, 0x9ff, s76
	s_cselect_b32 s76, s0, s76
	s_mul_hi_i32 s0, s76, 0x38e38e39
	s_lshr_b32 s1, s0, 31
	s_ashr_i32 s0, s0, 8
	s_add_i32 s0, s0, s1
	s_mulk_i32 s0, 0x480
	s_sub_i32 s26, s76, s0
	s_add_i32 s0, s76, 0x47f
	s_lshl_b32 s18, s26, 5
	s_cmpk_gt_u32 s0, 0x8fe
	s_mov_b64 s[0:1], -1
	s_cbranch_scc0 .LBB0_421
	s_add_i32 s0, s76, 0xfffffb80
	s_cmpk_gt_u32 s0, 0x47f
	s_mov_b64 s[0:1], -1
	s_cbranch_scc0 .LBB0_387
	s_mov_b64 s[8:9], s[30:31]
	v_mov_b32_e32 v0, v65
	s_sext_i32_i16 s4, s26
	v_mbcnt_lo_u32_b32 v0, -1, v0
	v_mbcnt_hi_u32_b32 v0, -1, v0
	v_add_u32_e32 v79, s33, v0
	v_mov_b32_e32 v0, s8
	v_mov_b32_e32 v1, s9
	v_add_co_u32_e32 v0, vcc, s55, v0
	s_mulk_i32 s4, 0xe39
	s_nop 0
	v_addc_co_u32_e32 v1, vcc, 0, v1, vcc
	global_load_dwordx2 v[0:1], v[0:1], off offset:504
	s_lshr_b32 s5, s4, 31
	s_ashr_i32 s13, s4, 18
	s_add_i32 s13, s13, s5
	s_add_u32 s10, s8, 0x7157900
	s_addc_u32 s11, s9, 0
	v_ashrrev_i32_e32 v36, 3, v79
	v_lshlrev_b32_e32 v78, 4, v79
	v_mov_b64_e32 v[12:13], s[10:11]
	v_add_u32_e32 v2, s18, v36
	v_and_b32_e32 v14, 0x70, v78
	v_mad_i64_i32 v[2:3], s[4:5], v2, s34, v[12:13]
	v_lshlrev_b32_e32 v64, 1, v14
	s_mov_b64 s[0:1], 0x1100
	v_lshl_add_u64 v[2:3], v[2:3], 0, v[64:65]
	v_lshl_add_u64 v[4:5], v[2:3], 0, s[0:1]
	v_add_co_u32_e32 v2, vcc, s35, v2
	global_load_dwordx4 v[8:11], v[4:5], off offset:16
	s_nop 0
	v_addc_co_u32_e32 v3, vcc, 0, v3, vcc
	global_load_dwordx4 v[4:7], v[2:3], off offset:256
	v_mov_b32_e32 v3, v65
	v_lshlrev_b32_e32 v2, 2, v14
	s_waitcnt lgkmcnt(0)
	s_barrier
	v_ashrrev_i32_e32 v81, 5, v79
	v_add_u32_e32 v66, s18, v81
	v_and_b32_e32 v80, 31, v79
	v_cmp_gt_u32_e64 s[6:7], 16, v80
	s_waitcnt vmcnt(0)
	v_readfirstlane_b32 s1, v1
	v_readfirstlane_b32 s0, v0
	v_lshlrev_b32_e32 v15, 16, v9
	s_nop 0
	v_lshl_add_u64 v[18:19], s[0:1], 0, v[2:3]
	global_load_dwordx4 v[0:3], v[18:19], off
	global_load_dwordx4 v[20:23], v[18:19], off offset:16
	v_and_b32_e32 v27, 0xffff0000, v5
	v_and_b32_e32 v26, 0xffff0000, v4
	v_lshlrev_b32_e32 v25, 16, v5
	v_lshlrev_b32_e32 v24, 16, v4
	v_and_b32_e32 v31, 0xffff0000, v7
	v_and_b32_e32 v30, 0xffff0000, v6
	v_pk_mul_f32 v[32:33], v[26:27], v[26:27]
	v_lshlrev_b32_e32 v29, 16, v7
	v_lshlrev_b32_e32 v28, 16, v6
	v_pk_mul_f32 v[34:35], v[30:31], v[30:31]
	v_pk_fma_f32 v[32:33], v[24:25], v[24:25], v[32:33]
	v_lshlrev_b32_e32 v14, 16, v8
	v_and_b32_e32 v9, 0xffff0000, v9
	v_and_b32_e32 v8, 0xffff0000, v8
	v_pk_fma_f32 v[34:35], v[28:29], v[28:29], v[34:35]
	v_add_f32_e32 v32, v32, v33
	v_pk_mul_f32 v[4:5], v[8:9], v[8:9]
	v_add_f32_e32 v32, v34, v32
	v_lshlrev_b32_e32 v17, 16, v11
	v_lshlrev_b32_e32 v16, 16, v10
	v_and_b32_e32 v11, 0xffff0000, v11
	v_and_b32_e32 v10, 0xffff0000, v10
	v_pk_fma_f32 v[4:5], v[14:15], v[14:15], v[4:5]
	v_add_f32_e32 v32, v35, v32
	v_pk_mul_f32 v[6:7], v[10:11], v[10:11]
	v_add_f32_e32 v4, v4, v32
	v_pk_fma_f32 v[6:7], v[16:17], v[16:17], v[6:7]
	v_add_f32_e32 v4, v5, v4
	v_add_f32_e32 v4, v6, v4
	v_add_f32_e32 v4, v7, v4
	s_waitcnt vmcnt(0) lgkmcnt(0)
	v_mov_b32_e32 v32, v0
	v_add_f32_dpp v4, v4, v4 quad_perm:[1,0,3,2] row_mask:0xf bank_mask:0xf bound_ctrl:1
	v_mov_b32_e32 v33, v2
	v_mov_b32_e32 v2, v1
	v_add_f32_dpp v4, v4, v4 quad_perm:[2,3,0,1] row_mask:0xf bank_mask:0xf bound_ctrl:1
	v_mov_b32_e32 v0, v20
	v_mov_b32_e32 v1, v22
	v_add_f32_dpp v4, v4, v4 row_half_mirror row_mask:0xf bank_mask:0xf bound_ctrl:1
	v_fmamk_f32 v4, v4, 0x3c000000, v127
	v_mul_f32_e32 v5, 0x4b800000, v4
	v_cmp_gt_f32_e32 vcc, s57, v4
	v_mov_b32_e32 v22, v21
	s_nop 0
	v_cndmask_b32_e32 v4, v4, v5, vcc
	v_rsq_f32_e32 v6, v4
	v_mad_u64_u32 v[4:5], s[0:1], v36, s56, v[64:65]
	v_lshlrev_b32_e32 v64, 1, v80
	v_mul_f32_e32 v5, 0x45800000, v6
	v_cndmask_b32_e32 v6, v6, v5, vcc
	v_pk_mul_f32 v[24:25], v[6:7], v[24:25] op_sel_hi:[0,1]
	v_pk_mul_f32 v[26:27], v[6:7], v[26:27] op_sel_hi:[0,1]
	v_pk_mul_f32 v[28:29], v[6:7], v[28:29] op_sel_hi:[0,1]
	v_pk_mul_f32 v[30:31], v[6:7], v[30:31] op_sel_hi:[0,1]
	v_pk_mul_f32 v[20:21], v[32:33], v[24:25]
	v_pk_mul_f32 v[2:3], v[2:3], v[26:27]
	v_pk_mul_f32 v[0:1], v[0:1], v[28:29]
	v_pk_mul_f32 v[22:23], v[22:23], v[30:31]
	v_bfe_u32 v24, v3, 16, 1
	v_bfe_u32 v5, v23, 16, 1
	v_bfe_u32 v7, v22, 16, 1
	v_bfe_u32 v25, v2, 16, 1
	v_bfe_u32 v26, v20, 16, 1
	v_bfe_u32 v27, v21, 16, 1
	v_bfe_u32 v28, v0, 16, 1
	v_bfe_u32 v29, v1, 16, 1
	v_add3_u32 v25, v2, v25, s58
	v_add3_u32 v24, v3, v24, s58
	v_add3_u32 v2, v22, v7, s58
	v_add3_u32 v3, v23, v5, s58
	v_add3_u32 v1, v1, v29, s58
	v_add3_u32 v0, v0, v28, s58
	v_add3_u32 v5, v21, v27, s58
	v_add3_u32 v7, v20, v26, s58
	v_lshrrev_b32_e32 v7, 16, v7
	v_lshrrev_b32_e32 v5, 16, v5
	v_lshrrev_b32_e32 v0, 16, v0
	v_lshrrev_b32_e32 v1, 16, v1
	v_and_or_b32 v3, v3, s54, v1
	v_and_or_b32 v2, v2, s54, v0
	v_and_or_b32 v1, v24, s54, v5
	v_and_or_b32 v0, v25, s54, v7
	ds_write_b128 v4, v[0:3]
	global_load_dwordx4 v[20:23], v[18:19], off offset:32
	global_load_dwordx4 v[24:27], v[18:19], off offset:48
	v_mad_i64_i32 v[0:1], s[0:1], v66, s34, v[12:13]
	v_pk_mul_f32 v[12:13], v[6:7], v[14:15] op_sel_hi:[0,1]
	v_pk_mul_f32 v[8:9], v[6:7], v[8:9] op_sel_hi:[0,1]
	v_pk_mul_f32 v[14:15], v[6:7], v[16:17] op_sel_hi:[0,1]
	v_pk_mul_f32 v[6:7], v[6:7], v[10:11] op_sel_hi:[0,1]
	v_lshl_add_u64 v[0:1], v[0:1], 0, s[20:21]
	v_lshl_add_u64 v[2:3], v[0:1], 0, v[64:65]
	s_mul_i32 s0, s13, 0xfffff700
	s_add_i32 s12, s0, s18
	s_cmpk_gt_i32 s12, 0xff
	s_cselect_b64 s[24:25], -1, 0
	s_cmpk_lt_i32 s12, 0x100
	s_waitcnt vmcnt(0) lgkmcnt(0)
	v_mov_b32_e32 v10, v20
	v_mov_b32_e32 v11, v22
	v_mov_b32_e32 v22, v21
	v_mov_b32_e32 v16, v24
	v_mov_b32_e32 v17, v26
	v_mov_b32_e32 v26, v25
	v_pk_mul_f32 v[10:11], v[10:11], v[12:13]
	v_pk_mul_f32 v[8:9], v[22:23], v[8:9]
	v_pk_mul_f32 v[12:13], v[16:17], v[14:15]
	v_pk_mul_f32 v[6:7], v[6:7], v[26:27]
	v_bfe_u32 v15, v9, 16, 1
	v_bfe_u32 v5, v7, 16, 1
	v_bfe_u32 v16, v8, 16, 1
	v_bfe_u32 v17, v10, 16, 1
	v_bfe_u32 v18, v11, 16, 1
	v_bfe_u32 v19, v12, 16, 1
	v_bfe_u32 v20, v13, 16, 1
	v_bfe_u32 v14, v6, 16, 1
	v_add3_u32 v16, v8, v16, s58
	v_add3_u32 v15, v9, v15, s58
	v_add3_u32 v5, v7, v5, s58
	v_add3_u32 v7, v13, v20, s58
	v_add3_u32 v8, v12, v19, s58
	v_add3_u32 v9, v11, v18, s58
	v_add3_u32 v10, v10, v17, s58
	v_add3_u32 v6, v6, v14, s58
	v_lshrrev_b32_e32 v10, 16, v10
	v_lshrrev_b32_e32 v11, 16, v9
	v_lshrrev_b32_e32 v8, 16, v8
	v_lshrrev_b32_e32 v7, 16, v7
	v_and_or_b32 v9, v5, s54, v7
	v_and_or_b32 v8, v6, s54, v8
	v_and_or_b32 v7, v15, s54, v11
	v_and_or_b32 v6, v16, s54, v10
	ds_write_b128 v4, v[6:9] offset:16
	global_load_ushort v2, v[2:3], off
	v_and_b32_e32 v4, 7, v79
	v_cvt_f32_ubyte0_e32 v4, v4
	v_mul_f32_e32 v6, 0xbfd49a78, v4
	v_cmp_gt_f32_e32 vcc, s59, v6
	v_and_b32_e32 v5, 8, v79
	v_bitop3_b32 v3, v79, 8, 31 bitop3:0x6c
	v_cndmask_b32_e32 v6, 0, v129, vcc
	v_fmac_f32_e32 v6, 0xbfd49a78, v4
	v_exp_f32_e32 v4, v6
	v_cmp_eq_u32_e64 s[4:5], 0, v5
	v_cndmask_b32_e32 v5, 0, v130, vcc
	v_ldexp_f32 v6, v4, v5
	s_waitcnt vmcnt(0) lgkmcnt(0)
	v_lshlrev_b32_e32 v4, 16, v2
	v_lshlrev_b32_e32 v2, 1, v3
	s_cbranch_scc1 .LBB0_380
	v_mov_b32_e32 v3, v65
	v_lshl_add_u64 v[0:1], v[0:1], 0, v[2:3]
	global_load_ushort v0, v[0:1], off
	v_add_u32_e32 v1, s12, v81
	v_add_u32_e32 v3, 0xffffff00, v1
	v_ashrrev_i32_e32 v3, 6, v3
	v_and_b32_e32 v1, 63, v1
	v_cndmask_b32_e64 v1, v1, v3, s[6:7]
	v_cvt_f32_i32_e32 v1, v1
	v_mul_f32_e32 v1, v6, v1
	v_mul_f32_e32 v1, 0.15915494, v1
	v_sin_f32_e32 v3, v1
	v_cos_f32_e32 v1, v1
	s_waitcnt vmcnt(0) lgkmcnt(0)
	v_lshlrev_b32_e32 v0, 16, v0
	v_mul_f32_e32 v0, v3, v0
	v_cndmask_b32_e64 v0, v0, -v0, s[4:5]
	v_fmac_f32_e32 v0, v1, v4
	v_mov_b32_e32 v4, v0

.LBB0_1357:
	s_sub_u32 s0, s78, 0x400
	s_cmp_lt_u32 s0, 0x200
	s_sub_i32 s0, 0x9ff, s78
	s_cselect_b32 s78, s0, s78
	s_add_i32 s78, s78, s94
	s_cmpk_lt_i32 s78, 0xd80
	s_cbranch_scc0 .LBB0_1353
.LBB0_1358:
	s_sub_u32 s0, s78, 0x400
	s_cmp_lt_u32 s0, 0x200
	s_sub_i32 s0, 0x9ff, s78
	s_cselect_b32 s78, s0, s78
	s_mul_hi_i32 s0, s78, 0x38e38e39
	s_lshr_b32 s1, s0, 31
	s_ashr_i32 s0, s0, 8
	s_add_i32 s0, s0, s1
	s_mulk_i32 s0, 0x480
	s_sub_i32 s26, s78, s0
	s_sext_i32_i16 s0, s26
	s_mulk_i32 s0, 0xe39
	s_lshr_b32 s1, s0, 31
	s_ashr_i32 s18, s0, 18
	s_add_i32 s18, s18, s1
	s_mul_i32 s0, s18, 0x48
	s_sub_i32 s0, s26, s0
	s_sext_i32_i16 s0, s0
	s_cmp_lt_i32 s0, 8
	s_cselect_b64 s[4:5], -1, 0
	s_add_i32 s6, s78, 0xfffffb80
	s_cmpk_gt_u32 s6, 0x47f
	s_cselect_b64 s[0:1], -1, 0
	s_cmpk_lt_u32 s6, 0x480
	s_cselect_b64 s[6:7], -1, 0
	s_and_b64 s[4:5], s[6:7], s[4:5]
	s_and_b64 vcc, exec, s[4:5]
	s_cbranch_vccnz .LBB0_1357
	s_add_i32 s4, s78, 0x47f
	s_cmpk_gt_u32 s4, 0x8fe
	s_mov_b64 s[4:5], -1
	s_cbranch_scc0 .LBB0_1404
	s_lshl_b32 s27, s26, 5
	s_and_b64 vcc, exec, s[0:1]
	s_cbranch_vccz .LBB0_1370
	s_mov_b64 s[8:9], s[30:31]
	v_mov_b32_e32 v0, v65
	s_add_u32 s10, s8, 0x7157900
	v_mbcnt_lo_u32_b32 v0, -1, v0
	v_mbcnt_hi_u32_b32 v0, -1, v0
	v_add_u32_e32 v79, s33, v0
	v_mov_b32_e32 v0, s8
	v_mov_b32_e32 v1, s9
	v_add_co_u32_e32 v0, vcc, s57, v0
	s_addc_u32 s11, s9, 0
	s_nop 0
	v_addc_co_u32_e32 v1, vcc, 0, v1, vcc
	global_load_dwordx2 v[0:1], v[0:1], off offset:504
	v_ashrrev_i32_e32 v36, 3, v79
	v_lshlrev_b32_e32 v78, 4, v79
	v_mov_b64_e32 v[12:13], s[10:11]
	v_add_u32_e32 v2, s27, v36
	v_and_b32_e32 v14, 0x70, v78
	v_mad_i64_i32 v[2:3], s[4:5], v2, s34, v[12:13]
	v_lshlrev_b32_e32 v64, 1, v14
	s_mov_b64 s[0:1], 0x1100
	v_lshl_add_u64 v[2:3], v[2:3], 0, v[64:65]
	v_lshl_add_u64 v[4:5], v[2:3], 0, s[0:1]
	v_add_co_u32_e32 v2, vcc, s35, v2
	global_load_dwordx4 v[8:11], v[4:5], off offset:16
	s_nop 0
	v_addc_co_u32_e32 v3, vcc, 0, v3, vcc
	global_load_dwordx4 v[4:7], v[2:3], off offset:256
	v_mov_b32_e32 v3, v65
	v_lshlrev_b32_e32 v2, 2, v14
	s_waitcnt lgkmcnt(0)
	s_barrier
	v_ashrrev_i32_e32 v81, 5, v79
	v_add_u32_e32 v66, s27, v81
	v_and_b32_e32 v80, 31, v79
	s_sext_i32_i16 s13, s18
	v_cmp_gt_u32_e64 s[6:7], 16, v80
	s_waitcnt vmcnt(0)
	v_readfirstlane_b32 s1, v1
	v_readfirstlane_b32 s0, v0
	v_lshlrev_b32_e32 v15, 16, v9
	s_nop 0
	v_lshl_add_u64 v[18:19], s[0:1], 0, v[2:3]
	global_load_dwordx4 v[0:3], v[18:19], off offset:512
	global_load_dwordx4 v[20:23], v[18:19], off offset:528
	v_and_b32_e32 v27, 0xffff0000, v5
	v_and_b32_e32 v26, 0xffff0000, v4
	v_lshlrev_b32_e32 v25, 16, v5
	v_lshlrev_b32_e32 v24, 16, v4
	v_and_b32_e32 v31, 0xffff0000, v7
	v_and_b32_e32 v30, 0xffff0000, v6
	v_pk_mul_f32 v[32:33], v[26:27], v[26:27]
	v_lshlrev_b32_e32 v29, 16, v7
	v_lshlrev_b32_e32 v28, 16, v6
	v_pk_mul_f32 v[34:35], v[30:31], v[30:31]
	v_pk_fma_f32 v[32:33], v[24:25], v[24:25], v[32:33]
	v_lshlrev_b32_e32 v14, 16, v8
	v_and_b32_e32 v9, 0xffff0000, v9
	v_and_b32_e32 v8, 0xffff0000, v8
	v_pk_fma_f32 v[34:35], v[28:29], v[28:29], v[34:35]
	v_add_f32_e32 v32, v32, v33
	v_pk_mul_f32 v[4:5], v[8:9], v[8:9]
	v_add_f32_e32 v32, v34, v32
	v_lshlrev_b32_e32 v17, 16, v11
	v_lshlrev_b32_e32 v16, 16, v10
	v_and_b32_e32 v11, 0xffff0000, v11
	v_and_b32_e32 v10, 0xffff0000, v10
	v_pk_fma_f32 v[4:5], v[14:15], v[14:15], v[4:5]
	v_add_f32_e32 v32, v35, v32
	v_pk_mul_f32 v[6:7], v[10:11], v[10:11]
	v_add_f32_e32 v4, v4, v32
	v_pk_fma_f32 v[6:7], v[16:17], v[16:17], v[6:7]
	v_add_f32_e32 v4, v5, v4
	v_add_f32_e32 v4, v6, v4
	v_add_f32_e32 v4, v7, v4
	s_waitcnt vmcnt(0) lgkmcnt(0)
	v_mov_b32_e32 v32, v0
	v_add_f32_dpp v4, v4, v4 quad_perm:[1,0,3,2] row_mask:0xf bank_mask:0xf bound_ctrl:1
	v_mov_b32_e32 v33, v2
	v_mov_b32_e32 v2, v1
	v_add_f32_dpp v4, v4, v4 quad_perm:[2,3,0,1] row_mask:0xf bank_mask:0xf bound_ctrl:1
	v_mov_b32_e32 v0, v20
	v_mov_b32_e32 v1, v22
	v_add_f32_dpp v4, v4, v4 row_half_mirror row_mask:0xf bank_mask:0xf bound_ctrl:1
	v_fmamk_f32 v4, v4, 0x3c000000, v127
	v_mul_f32_e32 v5, 0x4b800000, v4
	v_cmp_gt_f32_e32 vcc, s59, v4
	v_mov_b32_e32 v22, v21
	s_nop 0
	v_cndmask_b32_e32 v4, v4, v5, vcc
	v_rsq_f32_e32 v6, v4
	v_mad_u64_u32 v[4:5], s[0:1], v36, s58, v[64:65]
	v_lshlrev_b32_e32 v64, 1, v80
	v_mul_f32_e32 v5, 0x45800000, v6
	v_cndmask_b32_e32 v6, v6, v5, vcc
	v_pk_mul_f32 v[24:25], v[6:7], v[24:25] op_sel_hi:[0,1]
	v_pk_mul_f32 v[26:27], v[6:7], v[26:27] op_sel_hi:[0,1]
	v_pk_mul_f32 v[28:29], v[6:7], v[28:29] op_sel_hi:[0,1]
	v_pk_mul_f32 v[30:31], v[6:7], v[30:31] op_sel_hi:[0,1]
	v_pk_mul_f32 v[20:21], v[32:33], v[24:25]
	v_pk_mul_f32 v[2:3], v[2:3], v[26:27]
	v_pk_mul_f32 v[0:1], v[0:1], v[28:29]
	v_pk_mul_f32 v[22:23], v[22:23], v[30:31]
	v_bfe_u32 v24, v3, 16, 1
	v_bfe_u32 v5, v23, 16, 1
	v_bfe_u32 v7, v22, 16, 1
	v_bfe_u32 v25, v2, 16, 1
	v_bfe_u32 v26, v20, 16, 1
	v_bfe_u32 v27, v21, 16, 1
	v_bfe_u32 v28, v0, 16, 1
	v_bfe_u32 v29, v1, 16, 1
	v_add3_u32 v25, v2, v25, s60
	v_add3_u32 v24, v3, v24, s60
	v_add3_u32 v2, v22, v7, s60
	v_add3_u32 v3, v23, v5, s60
	v_add3_u32 v1, v1, v29, s60
	v_add3_u32 v0, v0, v28, s60
	v_add3_u32 v5, v21, v27, s60
	v_add3_u32 v7, v20, v26, s60
	v_lshrrev_b32_e32 v7, 16, v7
	v_lshrrev_b32_e32 v5, 16, v5
	v_lshrrev_b32_e32 v0, 16, v0
	v_lshrrev_b32_e32 v1, 16, v1
	v_and_or_b32 v3, v3, s56, v1
	v_and_or_b32 v2, v2, s56, v0
	v_and_or_b32 v1, v24, s56, v5
	v_and_or_b32 v0, v25, s56, v7
	ds_write_b128 v4, v[0:3]
	global_load_dwordx4 v[20:23], v[18:19], off offset:544
	global_load_dwordx4 v[24:27], v[18:19], off offset:560
	v_mad_i64_i32 v[0:1], s[0:1], v66, s34, v[12:13]
	v_pk_mul_f32 v[12:13], v[6:7], v[14:15] op_sel_hi:[0,1]
	v_pk_mul_f32 v[8:9], v[6:7], v[8:9] op_sel_hi:[0,1]
	v_pk_mul_f32 v[14:15], v[6:7], v[16:17] op_sel_hi:[0,1]
	v_pk_mul_f32 v[6:7], v[6:7], v[10:11] op_sel_hi:[0,1]
	v_lshl_add_u64 v[0:1], v[0:1], 0, s[20:21]
	v_lshl_add_u64 v[2:3], v[0:1], 0, v[64:65]
	s_mul_i32 s0, s13, 0xfffff700
	s_add_i32 s12, s0, s27
	s_cmpk_gt_i32 s12, 0xff
	s_cselect_b64 s[24:25], -1, 0
	s_cmpk_lt_i32 s12, 0x100
	s_waitcnt vmcnt(0) lgkmcnt(0)
	v_mov_b32_e32 v10, v20
	v_mov_b32_e32 v11, v22
	v_mov_b32_e32 v22, v21
	v_mov_b32_e32 v16, v24
	v_mov_b32_e32 v17, v26
	v_mov_b32_e32 v26, v25
	v_pk_mul_f32 v[10:11], v[10:11], v[12:13]
	v_pk_mul_f32 v[8:9], v[22:23], v[8:9]
	v_pk_mul_f32 v[12:13], v[16:17], v[14:15]
	v_pk_mul_f32 v[6:7], v[6:7], v[26:27]
	v_bfe_u32 v15, v9, 16, 1
	v_bfe_u32 v5, v7, 16, 1
	v_bfe_u32 v16, v8, 16, 1
	v_bfe_u32 v17, v10, 16, 1
	v_bfe_u32 v18, v11, 16, 1
	v_bfe_u32 v19, v12, 16, 1
	v_bfe_u32 v20, v13, 16, 1
	v_bfe_u32 v14, v6, 16, 1
	v_add3_u32 v16, v8, v16, s60
	v_add3_u32 v15, v9, v15, s60
	v_add3_u32 v5, v7, v5, s60
	v_add3_u32 v7, v13, v20, s60
	v_add3_u32 v8, v12, v19, s60
	v_add3_u32 v9, v11, v18, s60
	v_add3_u32 v10, v10, v17, s60
	v_add3_u32 v6, v6, v14, s60
	v_lshrrev_b32_e32 v10, 16, v10
	v_lshrrev_b32_e32 v11, 16, v9
	v_lshrrev_b32_e32 v8, 16, v8
	v_lshrrev_b32_e32 v7, 16, v7
	v_and_or_b32 v9, v5, s56, v7
	v_and_or_b32 v8, v6, s56, v8
	v_and_or_b32 v7, v15, s56, v11
	v_and_or_b32 v6, v16, s56, v10
	ds_write_b128 v4, v[6:9] offset:16
	global_load_ushort v2, v[2:3], off
	v_and_b32_e32 v4, 7, v79
	v_cvt_f32_ubyte0_e32 v4, v4
	v_mul_f32_e32 v6, 0xbfd49a78, v4
	v_cmp_gt_f32_e32 vcc, s61, v6
	v_and_b32_e32 v5, 8, v79
	v_bitop3_b32 v3, v79, 8, 31 bitop3:0x6c
	v_cndmask_b32_e32 v6, 0, v129, vcc
	v_fmac_f32_e32 v6, 0xbfd49a78, v4
	v_exp_f32_e32 v4, v6
	v_cmp_eq_u32_e64 s[4:5], 0, v5
	v_cndmask_b32_e32 v5, 0, v130, vcc
	v_ldexp_f32 v6, v4, v5
	s_waitcnt vmcnt(0) lgkmcnt(0)
	v_lshlrev_b32_e32 v4, 16, v2
	v_lshlrev_b32_e32 v2, 1, v3
	s_cbranch_scc1 .LBB0_1363
	v_mov_b32_e32 v3, v65
	v_lshl_add_u64 v[0:1], v[0:1], 0, v[2:3]
	global_load_ushort v0, v[0:1], off
	v_add_u32_e32 v1, s12, v81
	v_add_u32_e32 v3, 0xffffff00, v1
	v_ashrrev_i32_e32 v3, 6, v3
	v_and_b32_e32 v1, 63, v1
	v_cndmask_b32_e64 v1, v1, v3, s[6:7]
	v_cvt_f32_i32_e32 v1, v1
	v_mul_f32_e32 v1, v6, v1
	v_mul_f32_e32 v1, 0.15915494, v1
	v_sin_f32_e32 v3, v1
	v_cos_f32_e32 v1, v1
	s_waitcnt vmcnt(0) lgkmcnt(0)
	v_lshlrev_b32_e32 v0, 16, v0
	v_mul_f32_e32 v0, v3, v0
	v_cndmask_b32_e64 v0, v0, -v0, s[4:5]
	v_fmac_f32_e32 v0, v1, v4
	v_mov_b32_e32 v4, v0
